# DSA indexer: next key tile MFMAs issued before the current tile VALU (2 accumulator sets), pads removed (on top of v13)
# speedup vs baseline: 1.0047x; 1.0047x over previous
; #define IDX_LOAD(BUF, G) do { _Pragma("unroll") for (int tt = 0; tt < 4; ++tt) _Pragma("unroll") for (int ks = 0; ks < 2; ++ks) \
;                 BUF[tt][ks] = *(const bf16x8*)(ikb + (size_t)(((G) * 4 + tt) * 8 + ks * 4) * 128); } while (0)
; template <bool DUMMY> __device__ __forceinline__ void phase_dsa(const Args& a, unsigned char* lds) {
;     ...
;             int g = wave;
;             for (; g < ngroups; g += 24) {
;                 IDX_COMPUTE(B0, g);
;                 if (g + 24 < ngroups) IDX_LOAD(B0, g + 24);
;                 if (g + 8 < ngroups) { IDX_COMPUTE(B1, g + 8); if (g + 32 < ngroups) IDX_LOAD(B1, g + 32); }
;                 if (g + 16 < ngroups) { IDX_COMPUTE(B2, g + 16); if (g + 40 < ngroups) IDX_LOAD(B2, g + 40); }
.LBB0_868:
	s_waitcnt vmcnt(3)
	v_mfma_f32_16x16x32_bf16 v[136:139], v[108:111], v[12:15], 0
	s_and_b64 vcc, exec, s[6:7]
	s_waitcnt vmcnt(1)
	v_mfma_f32_16x16x32_bf16 v[140:143], v[116:119], v[12:15], 0
	v_mfma_f32_16x16x32_bf16 v[136:139], v[112:115], v[32:35], v[136:139]
	s_waitcnt vmcnt(0)
	v_mfma_f32_16x16x32_bf16 v[140:143], v[120:123], v[32:35], v[140:143]
	v_mfma_f32_16x16x32_bf16 v[144:147], v[108:111], v[52:55], 0
	v_mfma_f32_16x16x32_bf16 v[148:151], v[116:119], v[52:55], 0
	v_mfma_f32_16x16x32_bf16 v[144:147], v[112:115], v[56:59], v[144:147]
	v_mfma_f32_16x16x32_bf16 v[148:151], v[120:123], v[56:59], v[148:151]
	s_nop 5
	v_max_i32_e32 v135, 0, v136
	v_fma_f32 v135, v126, v135, 0
	v_max_i32_e32 v136, 0, v140
	v_fmac_f32_e32 v135, v127, v136
	v_max_i32_e32 v136, 0, v137
	v_fmac_f32_e32 v135, v128, v136
	v_max_i32_e32 v136, 0, v141
	v_fmac_f32_e32 v135, v129, v136
	v_max_i32_e32 v136, 0, v138
	v_fmac_f32_e32 v135, v130, v136
	v_max_i32_e32 v136, 0, v142
	v_fmac_f32_e32 v135, v131, v136
	v_max_i32_e32 v136, 0, v139
	v_fmac_f32_e32 v135, v132, v136
	v_max_i32_e32 v136, 0, v143
	v_fmac_f32_e32 v135, v133, v136
	v_add_f32_e32 v135, 0, v135
	ds_write_b32 v134, v135
	s_cbranch_vccz .LBB0_870
	v_not_b32_e32 v136, v135
	v_or_b32_e32 v137, 0x80000000, v135
	v_cmp_gt_i32_e32 vcc, 0, v135
	s_nop 1
	v_cndmask_b32_e32 v135, v137, v136, vcc
	v_alignbit_b32 v136, v8, v135, 22
	v_and_b32_e32 v135, 0x200000, v135
	v_lshl_add_u32 v136, v136, 2, 0
	v_cmp_eq_u32_e32 vcc, 0, v135
	v_add_u32_e32 v136, 0x20080, v136
	s_nop 0
	v_cndmask_b32_e64 v135, v217, 1, vcc
	ds_add_u32 v136, v135
.LBB0_870:
	v_mfma_f32_16x16x32_bf16 v[136:139], v[108:111], v[76:79], 0
	v_mfma_f32_16x16x32_bf16 v[140:143], v[116:119], v[76:79], 0
	v_mfma_f32_16x16x32_bf16 v[136:139], v[112:115], v[80:83], v[136:139]
	v_mfma_f32_16x16x32_bf16 v[140:143], v[120:123], v[80:83], v[140:143]
	s_andn2_b64 vcc, exec, s[6:7]
	v_max_i32_e32 v135, 0, v144
	v_fma_f32 v135, v126, v135, 0
	v_max_i32_e32 v144, 0, v148
	v_fmac_f32_e32 v135, v127, v144
	v_max_i32_e32 v144, 0, v145
	v_fmac_f32_e32 v135, v128, v144
	v_max_i32_e32 v144, 0, v149
	v_fmac_f32_e32 v135, v129, v144
	v_max_i32_e32 v144, 0, v146
	v_fmac_f32_e32 v135, v130, v144
	v_max_i32_e32 v144, 0, v150
	v_fmac_f32_e32 v135, v131, v144
	v_max_i32_e32 v144, 0, v147
	v_fmac_f32_e32 v135, v132, v144
	v_max_i32_e32 v144, 0, v151
	v_fmac_f32_e32 v135, v133, v144
	v_cndmask_b32_e64 v144, 0, 1, s[6:7]
	v_add_f32_e32 v135, 0, v135
	v_cmp_ne_u32_e64 s[4:5], 1, v144
	ds_write_b32 v134, v135 offset:64
	s_cbranch_vccnz .LBB0_872
	v_not_b32_e32 v144, v135
	v_or_b32_e32 v145, 0x80000000, v135
	v_cmp_gt_i32_e32 vcc, 0, v135
	s_nop 1
	v_cndmask_b32_e32 v135, v145, v144, vcc
	v_alignbit_b32 v144, v8, v135, 22
	v_and_b32_e32 v135, 0x200000, v135
	v_lshl_add_u32 v144, v144, 2, 0
	v_cmp_eq_u32_e32 vcc, 0, v135
	v_add_u32_e32 v144, 0x20080, v144
	s_nop 0
	v_cndmask_b32_e64 v135, v217, 1, vcc
	ds_add_u32 v144, v135
.LBB0_872:
	v_mfma_f32_16x16x32_bf16 v[144:147], v[108:111], v[100:103], 0
	v_mfma_f32_16x16x32_bf16 v[148:151], v[116:119], v[100:103], 0
	v_mfma_f32_16x16x32_bf16 v[144:147], v[112:115], v[104:107], v[144:147]
	v_mfma_f32_16x16x32_bf16 v[148:151], v[120:123], v[104:107], v[148:151]
	s_and_b64 vcc, exec, s[4:5]
	v_max_i32_e32 v135, 0, v136
	v_fma_f32 v135, v126, v135, 0
	v_max_i32_e32 v136, 0, v140
	v_fmac_f32_e32 v135, v127, v136
	v_max_i32_e32 v136, 0, v137
	v_fmac_f32_e32 v135, v128, v136
	v_max_i32_e32 v136, 0, v141
	v_fmac_f32_e32 v135, v129, v136
	v_max_i32_e32 v136, 0, v138
	v_fmac_f32_e32 v135, v130, v136
	v_max_i32_e32 v136, 0, v142
	v_fmac_f32_e32 v135, v131, v136
	v_max_i32_e32 v136, 0, v139
	v_fmac_f32_e32 v135, v132, v136
	v_max_i32_e32 v136, 0, v143
	v_fmac_f32_e32 v135, v133, v136
	v_add_f32_e32 v135, 0, v135
	ds_write_b32 v134, v135 offset:128
	s_cbranch_vccnz .LBB0_874
	v_not_b32_e32 v136, v135
	v_or_b32_e32 v137, 0x80000000, v135
	v_cmp_gt_i32_e32 vcc, 0, v135
	s_nop 1
	v_cndmask_b32_e32 v135, v137, v136, vcc
	v_alignbit_b32 v136, v8, v135, 22
	v_and_b32_e32 v135, 0x200000, v135
	v_lshl_add_u32 v136, v136, 2, 0
	v_cmp_eq_u32_e32 vcc, 0, v135
	v_add_u32_e32 v136, 0x20080, v136
	s_nop 0
	v_cndmask_b32_e64 v135, v217, 1, vcc
	ds_add_u32 v136, v135
.LBB0_874:
	s_and_b64 vcc, exec, s[4:5]
	v_max_i32_e32 v135, 0, v144
	v_fma_f32 v135, v126, v135, 0
	v_max_i32_e32 v144, 0, v148
	v_fmac_f32_e32 v135, v127, v144
	v_max_i32_e32 v144, 0, v145
	v_fmac_f32_e32 v135, v128, v144
	v_max_i32_e32 v144, 0, v149
	v_fmac_f32_e32 v135, v129, v144
	v_max_i32_e32 v144, 0, v146
	v_fmac_f32_e32 v135, v130, v144
	v_max_i32_e32 v144, 0, v150
	v_fmac_f32_e32 v135, v131, v144
	v_max_i32_e32 v144, 0, v147
	v_fmac_f32_e32 v135, v132, v144
	v_max_i32_e32 v144, 0, v151
	v_fmac_f32_e32 v135, v133, v144
	v_add_f32_e32 v135, 0, v135
	ds_write_b32 v134, v135 offset:192
	s_cbranch_vccnz .LBB0_876
	v_not_b32_e32 v144, v135
	v_or_b32_e32 v145, 0x80000000, v135
	v_cmp_gt_i32_e32 vcc, 0, v135
	s_nop 1
	v_cndmask_b32_e32 v135, v145, v144, vcc
	v_alignbit_b32 v144, v8, v135, 22
	v_and_b32_e32 v135, 0x200000, v135
	v_lshl_add_u32 v144, v144, 2, 0
	v_cmp_eq_u32_e32 vcc, 0, v135
	v_add_u32_e32 v144, 0x20080, v144
	s_nop 0
	v_cndmask_b32_e64 v135, v217, 1, vcc
	ds_add_u32 v144, v135

; #define IDX_LOAD(BUF, G) do { _Pragma("unroll") for (int tt = 0; tt < 4; ++tt) _Pragma("unroll") for (int ks = 0; ks < 2; ++ks) \
;                 BUF[tt][ks] = *(const bf16x8*)(ikb + (size_t)(((G) * 4 + tt) * 8 + ks * 4) * 128); } while (0)
; template <bool DUMMY> __device__ __forceinline__ void phase_dsa(const Args& a, unsigned char* lds) {
;     ...
;             int g = wave;
;             for (; g < ngroups; g += 24) {
;                 IDX_COMPUTE(B0, g);
;                 if (g + 24 < ngroups) IDX_LOAD(B0, g + 24);
;                 if (g + 8 < ngroups) { IDX_COMPUTE(B1, g + 8); if (g + 32 < ngroups) IDX_LOAD(B1, g + 32); }
;                 if (g + 16 < ngroups) { IDX_COMPUTE(B2, g + 16); if (g + 40 < ngroups) IDX_LOAD(B2, g + 40); }
.LBB0_878:
	s_add_i32 s15, s9, 8
	s_cmp_ge_i32 s15, s13
	s_cbranch_scc1 .LBB0_889
	v_mfma_f32_16x16x32_bf16 v[136:139], v[108:111], v[16:19], 0
	s_and_b64 vcc, exec, s[6:7]
	v_mfma_f32_16x16x32_bf16 v[140:143], v[116:119], v[16:19], 0
	v_mfma_f32_16x16x32_bf16 v[136:139], v[112:115], v[20:23], v[136:139]
	v_mfma_f32_16x16x32_bf16 v[140:143], v[120:123], v[20:23], v[140:143]
	v_mfma_f32_16x16x32_bf16 v[144:147], v[108:111], v[36:39], 0
	v_mfma_f32_16x16x32_bf16 v[148:151], v[116:119], v[36:39], 0
	v_mfma_f32_16x16x32_bf16 v[144:147], v[112:115], v[40:43], v[144:147]
	v_mfma_f32_16x16x32_bf16 v[148:151], v[120:123], v[40:43], v[148:151]
	s_nop 6
	v_max_i32_e32 v135, 0, v136
	v_fma_f32 v135, v126, v135, 0
	v_max_i32_e32 v136, 0, v140
	v_fmac_f32_e32 v135, v127, v136
	v_max_i32_e32 v136, 0, v137
	v_fmac_f32_e32 v135, v128, v136
	v_max_i32_e32 v136, 0, v141
	v_fmac_f32_e32 v135, v129, v136
	v_max_i32_e32 v136, 0, v138
	v_fmac_f32_e32 v135, v130, v136
	v_max_i32_e32 v136, 0, v142
	v_fmac_f32_e32 v135, v131, v136
	v_max_i32_e32 v136, 0, v139
	v_fmac_f32_e32 v135, v132, v136
	v_max_i32_e32 v136, 0, v143
	v_fmac_f32_e32 v135, v133, v136
	v_add_f32_e32 v135, 0, v135
	ds_write_b32 v134, v135 offset:2048
	s_cbranch_vccz .LBB0_881
	v_not_b32_e32 v136, v135
	v_or_b32_e32 v137, 0x80000000, v135
	v_cmp_gt_i32_e32 vcc, 0, v135
	s_nop 1
	v_cndmask_b32_e32 v135, v137, v136, vcc
	v_alignbit_b32 v136, v8, v135, 22
	v_and_b32_e32 v135, 0x200000, v135
	v_lshl_add_u32 v136, v136, 2, 0
	v_cmp_eq_u32_e32 vcc, 0, v135
	v_add_u32_e32 v136, 0x20080, v136
	s_nop 0
	v_cndmask_b32_e64 v135, v217, 1, vcc
	ds_add_u32 v136, v135
.LBB0_881:
	v_mfma_f32_16x16x32_bf16 v[136:139], v[108:111], v[60:63], 0
	v_mfma_f32_16x16x32_bf16 v[140:143], v[116:119], v[60:63], 0
	v_mfma_f32_16x16x32_bf16 v[136:139], v[112:115], v[64:67], v[136:139]
	v_mfma_f32_16x16x32_bf16 v[140:143], v[120:123], v[64:67], v[140:143]
	s_and_b64 vcc, exec, s[4:5]
	v_max_i32_e32 v135, 0, v144
	v_fma_f32 v135, v126, v135, 0
	v_max_i32_e32 v144, 0, v148
	v_fmac_f32_e32 v135, v127, v144
	v_max_i32_e32 v144, 0, v145
	v_fmac_f32_e32 v135, v128, v144
	v_max_i32_e32 v144, 0, v149
	v_fmac_f32_e32 v135, v129, v144
	v_max_i32_e32 v144, 0, v146
	v_fmac_f32_e32 v135, v130, v144
	v_max_i32_e32 v144, 0, v150
	v_fmac_f32_e32 v135, v131, v144
	v_max_i32_e32 v144, 0, v147
	v_fmac_f32_e32 v135, v132, v144
	v_max_i32_e32 v144, 0, v151
	v_fmac_f32_e32 v135, v133, v144
	v_add_f32_e32 v135, 0, v135
	ds_write_b32 v134, v135 offset:2112
	s_cbranch_vccnz .LBB0_883
	v_not_b32_e32 v144, v135
	v_or_b32_e32 v145, 0x80000000, v135
	v_cmp_gt_i32_e32 vcc, 0, v135
	s_nop 1
	v_cndmask_b32_e32 v135, v145, v144, vcc
	v_alignbit_b32 v144, v8, v135, 22
	v_and_b32_e32 v135, 0x200000, v135
	v_lshl_add_u32 v144, v144, 2, 0
	v_cmp_eq_u32_e32 vcc, 0, v135
	v_add_u32_e32 v144, 0x20080, v144
	s_nop 0
	v_cndmask_b32_e64 v135, v217, 1, vcc
	ds_add_u32 v144, v135
.LBB0_883:
	v_mfma_f32_16x16x32_bf16 v[144:147], v[108:111], v[84:87], 0
	v_mfma_f32_16x16x32_bf16 v[148:151], v[116:119], v[84:87], 0
	v_mfma_f32_16x16x32_bf16 v[144:147], v[112:115], v[88:91], v[144:147]
	v_mfma_f32_16x16x32_bf16 v[148:151], v[120:123], v[88:91], v[148:151]
	s_and_b64 vcc, exec, s[4:5]
	v_max_i32_e32 v135, 0, v136
	v_fma_f32 v135, v126, v135, 0
	v_max_i32_e32 v136, 0, v140
	v_fmac_f32_e32 v135, v127, v136
	v_max_i32_e32 v136, 0, v137
	v_fmac_f32_e32 v135, v128, v136
	v_max_i32_e32 v136, 0, v141
	v_fmac_f32_e32 v135, v129, v136
	v_max_i32_e32 v136, 0, v138
	v_fmac_f32_e32 v135, v130, v136
	v_max_i32_e32 v136, 0, v142
	v_fmac_f32_e32 v135, v131, v136
	v_max_i32_e32 v136, 0, v139
	v_fmac_f32_e32 v135, v132, v136
	v_max_i32_e32 v136, 0, v143
	v_fmac_f32_e32 v135, v133, v136
	v_add_f32_e32 v135, 0, v135
	ds_write_b32 v134, v135 offset:2176
	s_cbranch_vccnz .LBB0_885
	v_not_b32_e32 v136, v135
	v_or_b32_e32 v137, 0x80000000, v135
	v_cmp_gt_i32_e32 vcc, 0, v135
	s_nop 1
	v_cndmask_b32_e32 v135, v137, v136, vcc
	v_alignbit_b32 v136, v8, v135, 22
	v_and_b32_e32 v135, 0x200000, v135
	v_lshl_add_u32 v136, v136, 2, 0
	v_cmp_eq_u32_e32 vcc, 0, v135
	v_add_u32_e32 v136, 0x20080, v136
	s_nop 0
	v_cndmask_b32_e64 v135, v217, 1, vcc
	ds_add_u32 v136, v135
.LBB0_885:
	s_and_b64 vcc, exec, s[4:5]
	v_max_i32_e32 v135, 0, v144
	v_fma_f32 v135, v126, v135, 0
	v_max_i32_e32 v144, 0, v148
	v_fmac_f32_e32 v135, v127, v144
	v_max_i32_e32 v144, 0, v145
	v_fmac_f32_e32 v135, v128, v144
	v_max_i32_e32 v144, 0, v149
	v_fmac_f32_e32 v135, v129, v144
	v_max_i32_e32 v144, 0, v146
	v_fmac_f32_e32 v135, v130, v144
	v_max_i32_e32 v144, 0, v150
	v_fmac_f32_e32 v135, v131, v144
	v_max_i32_e32 v144, 0, v147
	v_fmac_f32_e32 v135, v132, v144
	v_max_i32_e32 v144, 0, v151
	v_fmac_f32_e32 v135, v133, v144
	v_add_f32_e32 v135, 0, v135
	ds_write_b32 v134, v135 offset:2240
	s_cbranch_vccnz .LBB0_887
	v_not_b32_e32 v144, v135
	v_or_b32_e32 v145, 0x80000000, v135
	v_cmp_gt_i32_e32 vcc, 0, v135
	s_nop 1
	v_cndmask_b32_e32 v135, v145, v144, vcc
	v_alignbit_b32 v144, v8, v135, 22
	v_and_b32_e32 v135, 0x200000, v135
	v_lshl_add_u32 v144, v144, 2, 0
	v_cmp_eq_u32_e32 vcc, 0, v135
	v_add_u32_e32 v144, 0x20080, v144
	s_nop 0
	v_cndmask_b32_e64 v135, v217, 1, vcc
	ds_add_u32 v144, v135

; #define IDX_LOAD(BUF, G) do { _Pragma("unroll") for (int tt = 0; tt < 4; ++tt) _Pragma("unroll") for (int ks = 0; ks < 2; ++ks) \
;                 BUF[tt][ks] = *(const bf16x8*)(ikb + (size_t)(((G) * 4 + tt) * 8 + ks * 4) * 128); } while (0)
; template <bool DUMMY> __device__ __forceinline__ void phase_dsa(const Args& a, unsigned char* lds) {
;     ...
;             int g = wave;
;             for (; g < ngroups; g += 24) {
;                 IDX_COMPUTE(B0, g);
;                 if (g + 24 < ngroups) IDX_LOAD(B0, g + 24);
;                 if (g + 8 < ngroups) { IDX_COMPUTE(B1, g + 8); if (g + 32 < ngroups) IDX_LOAD(B1, g + 32); }
;                 if (g + 16 < ngroups) { IDX_COMPUTE(B2, g + 16); if (g + 40 < ngroups) IDX_LOAD(B2, g + 40); }
.LBB0_889:
	s_add_i32 s15, s9, 16
	s_cmp_ge_i32 s15, s13
	s_cbranch_scc1 .LBB0_900
	v_mfma_f32_16x16x32_bf16 v[136:139], v[108:111], v[24:27], 0
	s_and_b64 vcc, exec, s[6:7]
	v_mfma_f32_16x16x32_bf16 v[140:143], v[116:119], v[24:27], 0
	v_mfma_f32_16x16x32_bf16 v[136:139], v[112:115], v[28:31], v[136:139]
	v_mfma_f32_16x16x32_bf16 v[140:143], v[120:123], v[28:31], v[140:143]
	v_mfma_f32_16x16x32_bf16 v[144:147], v[108:111], v[44:47], 0
	v_mfma_f32_16x16x32_bf16 v[148:151], v[116:119], v[44:47], 0
	v_mfma_f32_16x16x32_bf16 v[144:147], v[112:115], v[48:51], v[144:147]
	v_mfma_f32_16x16x32_bf16 v[148:151], v[120:123], v[48:51], v[148:151]
	s_nop 6
	v_max_i32_e32 v135, 0, v136
	v_fma_f32 v135, v126, v135, 0
	v_max_i32_e32 v136, 0, v140
	v_fmac_f32_e32 v135, v127, v136
	v_max_i32_e32 v136, 0, v137
	v_fmac_f32_e32 v135, v128, v136
	v_max_i32_e32 v136, 0, v141
	v_fmac_f32_e32 v135, v129, v136
	v_max_i32_e32 v136, 0, v138
	v_fmac_f32_e32 v135, v130, v136
	v_max_i32_e32 v136, 0, v142
	v_fmac_f32_e32 v135, v131, v136
	v_max_i32_e32 v136, 0, v139
	v_fmac_f32_e32 v135, v132, v136
	v_max_i32_e32 v136, 0, v143
	v_fmac_f32_e32 v135, v133, v136
	v_add_f32_e32 v135, 0, v135
	ds_write_b32 v134, v135 offset:4096
	s_cbranch_vccz .LBB0_892
	v_not_b32_e32 v136, v135
	v_or_b32_e32 v137, 0x80000000, v135
	v_cmp_gt_i32_e32 vcc, 0, v135
	s_nop 1
	v_cndmask_b32_e32 v135, v137, v136, vcc
	v_alignbit_b32 v136, v8, v135, 22
	v_and_b32_e32 v135, 0x200000, v135
	v_lshl_add_u32 v136, v136, 2, 0
	v_cmp_eq_u32_e32 vcc, 0, v135
	v_add_u32_e32 v136, 0x20080, v136
	s_nop 0
	v_cndmask_b32_e64 v135, v217, 1, vcc
	ds_add_u32 v136, v135
.LBB0_892:
	v_mfma_f32_16x16x32_bf16 v[136:139], v[108:111], v[68:71], 0
	v_mfma_f32_16x16x32_bf16 v[140:143], v[116:119], v[68:71], 0
	v_mfma_f32_16x16x32_bf16 v[136:139], v[112:115], v[72:75], v[136:139]
	v_mfma_f32_16x16x32_bf16 v[140:143], v[120:123], v[72:75], v[140:143]
	s_and_b64 vcc, exec, s[4:5]
	v_max_i32_e32 v135, 0, v144
	v_fma_f32 v135, v126, v135, 0
	v_max_i32_e32 v144, 0, v148
	v_fmac_f32_e32 v135, v127, v144
	v_max_i32_e32 v144, 0, v145
	v_fmac_f32_e32 v135, v128, v144
	v_max_i32_e32 v144, 0, v149
	v_fmac_f32_e32 v135, v129, v144
	v_max_i32_e32 v144, 0, v146
	v_fmac_f32_e32 v135, v130, v144
	v_max_i32_e32 v144, 0, v150
	v_fmac_f32_e32 v135, v131, v144
	v_max_i32_e32 v144, 0, v147
	v_fmac_f32_e32 v135, v132, v144
	v_max_i32_e32 v144, 0, v151
	v_fmac_f32_e32 v135, v133, v144
	v_add_f32_e32 v135, 0, v135
	ds_write_b32 v134, v135 offset:4160
	s_cbranch_vccnz .LBB0_894
	v_not_b32_e32 v144, v135
	v_or_b32_e32 v145, 0x80000000, v135
	v_cmp_gt_i32_e32 vcc, 0, v135
	s_nop 1
	v_cndmask_b32_e32 v135, v145, v144, vcc
	v_alignbit_b32 v144, v8, v135, 22
	v_and_b32_e32 v135, 0x200000, v135
	v_lshl_add_u32 v144, v144, 2, 0
	v_cmp_eq_u32_e32 vcc, 0, v135
	v_add_u32_e32 v144, 0x20080, v144
	s_nop 0
	v_cndmask_b32_e64 v135, v217, 1, vcc
	ds_add_u32 v144, v135
.LBB0_894:
	v_mfma_f32_16x16x32_bf16 v[144:147], v[108:111], v[92:95], 0
	v_mfma_f32_16x16x32_bf16 v[148:151], v[116:119], v[92:95], 0
	v_mfma_f32_16x16x32_bf16 v[144:147], v[112:115], v[96:99], v[144:147]
	v_mfma_f32_16x16x32_bf16 v[148:151], v[120:123], v[96:99], v[148:151]
	s_and_b64 vcc, exec, s[4:5]
	v_max_i32_e32 v135, 0, v136
	v_fma_f32 v135, v126, v135, 0
	v_max_i32_e32 v136, 0, v140
	v_fmac_f32_e32 v135, v127, v136
	v_max_i32_e32 v136, 0, v137
	v_fmac_f32_e32 v135, v128, v136
	v_max_i32_e32 v136, 0, v141
	v_fmac_f32_e32 v135, v129, v136
	v_max_i32_e32 v136, 0, v138
	v_fmac_f32_e32 v135, v130, v136
	v_max_i32_e32 v136, 0, v142
	v_fmac_f32_e32 v135, v131, v136
	v_max_i32_e32 v136, 0, v139
	v_fmac_f32_e32 v135, v132, v136
	v_max_i32_e32 v136, 0, v143
	v_fmac_f32_e32 v135, v133, v136
	v_add_f32_e32 v135, 0, v135
	ds_write_b32 v134, v135 offset:4224
	s_cbranch_vccnz .LBB0_896
	v_not_b32_e32 v136, v135
	v_or_b32_e32 v137, 0x80000000, v135
	v_cmp_gt_i32_e32 vcc, 0, v135
	s_nop 1
	v_cndmask_b32_e32 v135, v137, v136, vcc
	v_alignbit_b32 v136, v8, v135, 22
	v_and_b32_e32 v135, 0x200000, v135
	v_lshl_add_u32 v136, v136, 2, 0
	v_cmp_eq_u32_e32 vcc, 0, v135
	v_add_u32_e32 v136, 0x20080, v136
	s_nop 0
	v_cndmask_b32_e64 v135, v217, 1, vcc
	ds_add_u32 v136, v135
.LBB0_896:
	s_and_b64 vcc, exec, s[4:5]
	v_max_i32_e32 v135, 0, v144
	v_fma_f32 v135, v126, v135, 0
	v_max_i32_e32 v144, 0, v148
	v_fmac_f32_e32 v135, v127, v144
	v_max_i32_e32 v144, 0, v145
	v_fmac_f32_e32 v135, v128, v144
	v_max_i32_e32 v144, 0, v149
	v_fmac_f32_e32 v135, v129, v144
	v_max_i32_e32 v144, 0, v146
	v_fmac_f32_e32 v135, v130, v144
	v_max_i32_e32 v144, 0, v150
	v_fmac_f32_e32 v135, v131, v144
	v_max_i32_e32 v144, 0, v147
	v_fmac_f32_e32 v135, v132, v144
	v_max_i32_e32 v144, 0, v151
	v_fmac_f32_e32 v135, v133, v144
	v_add_f32_e32 v135, 0, v135
	ds_write_b32 v134, v135 offset:4288
	s_cbranch_vccnz .LBB0_898
	v_not_b32_e32 v144, v135
	v_or_b32_e32 v145, 0x80000000, v135
	v_cmp_gt_i32_e32 vcc, 0, v135
	s_nop 1
	v_cndmask_b32_e32 v135, v145, v144, vcc
	v_alignbit_b32 v144, v8, v135, 22
	v_and_b32_e32 v135, 0x200000, v135
	v_lshl_add_u32 v144, v144, 2, 0
	v_cmp_eq_u32_e32 vcc, 0, v135
	v_add_u32_e32 v144, 0x20080, v144
	s_nop 0
	v_cndmask_b32_e64 v135, v217, 1, vcc
	ds_add_u32 v144, v135
